# post (group-norm) phase row loop software-pipelined: next row's 24 loads issued into a landing register set before the current row's compute, ladder waits replaced by one counted wait
# baseline (speedup 1.0000x reference)
.LBB0_500:
	s_andn2_b64 vcc, exec, s[0:1]
	s_cbranch_vccnz .LBB0_505
	v_readlane_b32 s0, v254, 1
	s_lshl_b32 s0, s0, 11
	s_ashr_i32 s1, s0, 31
	v_readlane_b32 s80, v252, 40
	s_waitcnt vmcnt(0)
	v_mov_b32_e32 v6, v250
	s_lshl_b64 s[0:1], s[0:1], 2
	v_readlane_b32 s92, v252, 52
	v_readlane_b32 s93, v252, 53
	s_add_u32 s0, s92, s0
	v_lshlrev_b32_e32 v0, 2, v6
	s_addc_u32 s1, s93, s1
	v_ashrrev_i32_e32 v1, 31, v0
	v_lshl_add_u64 v[2:3], v[0:1], 2, s[0:1]
	s_waitcnt lgkmcnt(0)
	s_barrier
	global_load_dwordx4 v[2:5], v[2:3], off
	v_ashrrev_i32_e32 v7, 6, v6
	v_readlane_b32 s0, v253, 28
	v_lshlrev_b32_e32 v1, 4, v6
	v_readlane_b32 s81, v252, 41
	v_add_u32_e32 v82, s0, v7
	s_movk_i32 s0, 0x2000
	v_cmp_gt_i32_e32 vcc, s0, v82
	v_readlane_b32 s82, v252, 42
	v_readlane_b32 s83, v252, 43
	v_readlane_b32 s84, v252, 44
	v_readlane_b32 s85, v252, 45
	v_readlane_b32 s86, v252, 46
	v_readlane_b32 s87, v252, 47
	v_readlane_b32 s88, v252, 48
	v_readlane_b32 s89, v252, 49
	v_readlane_b32 s90, v252, 50
	v_readlane_b32 s91, v252, 51
	v_readlane_b32 s94, v252, 54
	v_readlane_b32 s95, v252, 55
	s_waitcnt vmcnt(0)
	ds_write_b128 v1, v[2:5]
	s_waitcnt lgkmcnt(0)
	s_barrier
	s_and_saveexec_b64 s[4:5], vcc
	v_readlane_b32 s10, v253, 24
	v_readlane_b32 s12, v253, 26
	v_readlane_b32 s11, v253, 25
	v_readlane_b32 s13, v253, 27
	v_readlane_b32 s14, v253, 29
	s_movk_i32 s15, 0x840
	s_mov_b32 s34, 0x3b800000
	s_cbranch_execz .LBB0_504
	v_and_b32_e32 v8, 0xfc, v0
	v_and_b32_e32 v0, 64, v181
	v_add_u32_e32 v0, 64, v0
	v_xor_b32_e32 v1, 32, v181
	v_cmp_lt_i32_e32 vcc, v1, v0
	v_lshlrev_b32_e32 v83, 2, v8
	v_readlane_b32 s0, v253, 33
	v_cndmask_b32_e32 v1, v181, v1, vcc
	v_lshlrev_b32_e32 v84, 2, v1
	v_xor_b32_e32 v1, 16, v181
	v_cmp_lt_i32_e32 vcc, v1, v0
	v_lshlrev_b32_e32 v144, 1, v8
	v_readlane_b32 s1, v253, 34
	v_cndmask_b32_e32 v1, v181, v1, vcc
	v_lshlrev_b32_e32 v85, 2, v1
	v_xor_b32_e32 v1, 8, v181
	v_cmp_lt_i32_e32 vcc, v1, v0
	v_mov_b32_e32 v9, v145
	v_lshl_add_u64 v[10:11], s[0:1], 0, v[144:145]
	v_cndmask_b32_e32 v1, v181, v1, vcc
	v_lshlrev_b32_e32 v86, 2, v1
	v_xor_b32_e32 v1, 4, v181
	v_cmp_lt_i32_e32 vcc, v1, v0
	s_mov_b64 s[6:7], 0
	s_nop 0
	v_cndmask_b32_e32 v1, v181, v1, vcc
	v_lshlrev_b32_e32 v87, 2, v1
	v_xor_b32_e32 v1, 2, v181
	v_cmp_lt_i32_e32 vcc, v1, v0
	s_nop 1
	v_cndmask_b32_e32 v1, v181, v1, vcc
	v_lshlrev_b32_e32 v88, 2, v1
	v_xor_b32_e32 v1, 1, v181
	v_cmp_lt_i32_e32 vcc, v1, v0
	s_nop 1
	v_cndmask_b32_e32 v0, v181, v1, vcc
	v_lshlrev_b32_e32 v89, 2, v0
	ds_read_b128 v[0:3], v83
	v_mad_i64_i32 v[160:161], s[0:1], v82, s15, v[8:9]
	v_lshlrev_b64 v[160:161], 1, v[160:161]
	v_lshl_add_u64 v[162:163], s[12:13], 0, v[160:161]
	v_lshl_add_u64 v[160:161], s[10:11], 0, v[160:161]
	v_mov_b64_e32 v[164:165], s[76:77]
	v_mad_i64_i32 v[164:165], s[0:1], v82, s69, v[164:165]
	v_lshlrev_b32_e32 v166, 1, v8
	v_mov_b32_e32 v167, v145
	v_lshl_add_u64 v[164:165], v[164:165], 0, v[166:167]
	v_add_co_u32_e32 v164, vcc, 0xb9a3000, v164
	s_nop 1
	v_addc_co_u32_e32 v165, vcc, 0, v165, vcc
	global_load_dwordx2 v[106:107], v[160:161], off nt
	global_load_dwordx2 v[108:109], v[162:163], off nt
	global_load_dwordx2 v[110:111], v[164:165], off nt
	global_load_dwordx2 v[112:113], v[160:161], off offset:512 nt
	global_load_dwordx2 v[114:115], v[162:163], off offset:512 nt
	global_load_dwordx2 v[116:117], v[164:165], off offset:512 nt
	global_load_dwordx2 v[118:119], v[160:161], off offset:1024 nt
	global_load_dwordx2 v[120:121], v[162:163], off offset:1024 nt
	global_load_dwordx2 v[122:123], v[164:165], off offset:1024 nt
	global_load_dwordx2 v[124:125], v[160:161], off offset:1536 nt
	global_load_dwordx2 v[126:127], v[162:163], off offset:1536 nt
	global_load_dwordx2 v[128:129], v[164:165], off offset:1536 nt
	global_load_dwordx2 v[130:131], v[160:161], off offset:2048 nt
	global_load_dwordx2 v[132:133], v[162:163], off offset:2048 nt
	global_load_dwordx2 v[134:135], v[164:165], off offset:2048 nt
	global_load_dwordx2 v[136:137], v[160:161], off offset:2560 nt
	global_load_dwordx2 v[138:139], v[162:163], off offset:2560 nt
	global_load_dwordx2 v[140:141], v[164:165], off offset:2560 nt
	global_load_dwordx2 v[142:143], v[160:161], off offset:3072 nt
	global_load_dwordx2 v[148:149], v[162:163], off offset:3072 nt
	global_load_dwordx2 v[150:151], v[164:165], off offset:3072 nt
	global_load_dwordx2 v[152:153], v[160:161], off offset:3584 nt
	global_load_dwordx2 v[154:155], v[162:163], off offset:3584 nt
	global_load_dwordx2 v[156:157], v[164:165], off offset:3584 nt
	s_waitcnt vmcnt(0)
.LBB0_503:
	s_waitcnt vmcnt(8)
	v_mov_b64_e32 v[16:17], v[106:107]
	v_mov_b64_e32 v[22:23], v[108:109]
	v_mov_b64_e32 v[34:35], v[110:111]
	v_mov_b64_e32 v[24:25], v[112:113]
	v_mov_b64_e32 v[26:27], v[114:115]
	v_mov_b64_e32 v[76:77], v[116:117]
	v_mov_b64_e32 v[28:29], v[118:119]
	v_mov_b64_e32 v[30:31], v[120:121]
	v_mov_b64_e32 v[62:63], v[122:123]
	v_mov_b64_e32 v[32:33], v[124:125]
	v_mov_b64_e32 v[38:39], v[126:127]
	v_mov_b64_e32 v[56:57], v[128:129]
	v_mov_b64_e32 v[40:41], v[130:131]
	v_mov_b64_e32 v[46:47], v[132:133]
	v_mov_b64_e32 v[42:43], v[134:135]
	v_mov_b64_e32 v[48:49], v[136:137]
	v_mov_b64_e32 v[50:51], v[138:139]
	v_mov_b64_e32 v[36:37], v[140:141]
	v_mov_b64_e32 v[52:53], v[142:143]
	v_mov_b64_e32 v[54:55], v[148:149]
	v_mov_b64_e32 v[20:21], v[150:151]
	v_mov_b64_e32 v[14:15], v[152:153]
	v_mov_b64_e32 v[68:69], v[154:155]
	v_mov_b64_e32 v[18:19], v[156:157]
	v_lshlrev_b32_e32 v144, 1, v8
	v_add_u32_e32 v168, s14, v82
	v_cmp_gt_i32_e32 vcc, 0x2000, v168
	s_cbranch_vccz .Lpost_nonext
	v_mad_i64_i32 v[160:161], s[0:1], v168, s15, v[8:9]
	v_lshlrev_b64 v[160:161], 1, v[160:161]
	v_lshl_add_u64 v[162:163], s[12:13], 0, v[160:161]
	v_lshl_add_u64 v[160:161], s[10:11], 0, v[160:161]
	v_mov_b64_e32 v[164:165], s[76:77]
	v_mad_i64_i32 v[164:165], s[0:1], v168, s69, v[164:165]
	v_lshlrev_b32_e32 v166, 1, v8
	v_mov_b32_e32 v167, v145
	v_lshl_add_u64 v[164:165], v[164:165], 0, v[166:167]
	v_add_co_u32_e32 v164, vcc, 0xb9a3000, v164
	s_nop 1
	v_addc_co_u32_e32 v165, vcc, 0, v165, vcc
	global_load_dwordx2 v[106:107], v[160:161], off nt
	global_load_dwordx2 v[108:109], v[162:163], off nt
	global_load_dwordx2 v[110:111], v[164:165], off nt
	global_load_dwordx2 v[112:113], v[160:161], off offset:512 nt
	global_load_dwordx2 v[114:115], v[162:163], off offset:512 nt
	global_load_dwordx2 v[116:117], v[164:165], off offset:512 nt
	global_load_dwordx2 v[118:119], v[160:161], off offset:1024 nt
	global_load_dwordx2 v[120:121], v[162:163], off offset:1024 nt
	global_load_dwordx2 v[122:123], v[164:165], off offset:1024 nt
	global_load_dwordx2 v[124:125], v[160:161], off offset:1536 nt
	global_load_dwordx2 v[126:127], v[162:163], off offset:1536 nt
	global_load_dwordx2 v[128:129], v[164:165], off offset:1536 nt
	global_load_dwordx2 v[130:131], v[160:161], off offset:2048 nt
	global_load_dwordx2 v[132:133], v[162:163], off offset:2048 nt
	global_load_dwordx2 v[134:135], v[164:165], off offset:2048 nt
	global_load_dwordx2 v[136:137], v[160:161], off offset:2560 nt
	global_load_dwordx2 v[138:139], v[162:163], off offset:2560 nt
	global_load_dwordx2 v[140:141], v[164:165], off offset:2560 nt
	global_load_dwordx2 v[142:143], v[160:161], off offset:3072 nt
	global_load_dwordx2 v[148:149], v[162:163], off offset:3072 nt
	global_load_dwordx2 v[150:151], v[164:165], off offset:3072 nt
	global_load_dwordx2 v[152:153], v[160:161], off offset:3584 nt
	global_load_dwordx2 v[154:155], v[162:163], off offset:3584 nt
	global_load_dwordx2 v[156:157], v[164:165], off offset:3584 nt
.Lpost_nonext:
	v_lshlrev_b32_e32 v98, 16, v34
	v_mul_f32_e32 v100, 0xbfb8aa3b, v98
	v_exp_f32_e32 v100, v100
	v_and_b32_e32 v34, 0xffff0000, v34
	v_lshlrev_b32_e32 v99, 16, v35
	v_and_b32_e32 v35, 0xffff0000, v35
	v_add_f32_e32 v100, 1.0, v100
	v_lshlrev_b32_e32 v4, 16, v16
	v_and_b32_e32 v5, 0xffff0000, v16
	v_lshlrev_b32_e32 v6, 16, v22
	v_and_b32_e32 v7, 0xffff0000, v22
	v_pk_add_f32 v[4:5], v[4:5], v[6:7]
	v_lshlrev_b32_e32 v6, 16, v17
	v_and_b32_e32 v7, 0xffff0000, v17
	v_lshlrev_b32_e32 v12, 16, v23
	v_and_b32_e32 v13, 0xffff0000, v23
	v_pk_add_f32 v[6:7], v[6:7], v[12:13]
	v_add_f32_e32 v12, v4, v5
	v_add_f32_e32 v12, v6, v12
	v_add_f32_e32 v70, v7, v12
	v_lshlrev_b32_e32 v12, 16, v24
	v_and_b32_e32 v13, 0xffff0000, v24
	v_lshlrev_b32_e32 v16, 16, v26
	v_and_b32_e32 v17, 0xffff0000, v26
	v_pk_add_f32 v[80:81], v[12:13], v[16:17]
	v_lshlrev_b32_e32 v12, 16, v25
	v_and_b32_e32 v13, 0xffff0000, v25
	v_lshlrev_b32_e32 v16, 16, v27
	v_and_b32_e32 v17, 0xffff0000, v27
	v_pk_add_f32 v[78:79], v[12:13], v[16:17]
	v_add_f32_e32 v12, v80, v81
	v_add_f32_e32 v12, v78, v12
	v_add_f32_e32 v26, v79, v12
	v_lshlrev_b32_e32 v12, 16, v28
	v_and_b32_e32 v13, 0xffff0000, v28
	v_lshlrev_b32_e32 v16, 16, v30
	v_and_b32_e32 v17, 0xffff0000, v30
	v_pk_add_f32 v[64:65], v[12:13], v[16:17]
	v_lshlrev_b32_e32 v12, 16, v29
	v_and_b32_e32 v13, 0xffff0000, v29
	v_lshlrev_b32_e32 v16, 16, v31
	v_and_b32_e32 v17, 0xffff0000, v31
	v_pk_add_f32 v[66:67], v[12:13], v[16:17]
	v_add_f32_e32 v12, v64, v65
	v_add_f32_e32 v12, v66, v12
	v_add_f32_e32 v27, v67, v12
	v_lshlrev_b32_e32 v12, 16, v32
	v_and_b32_e32 v13, 0xffff0000, v32
	ds_bpermute_b32 v32, v84, v26
	v_lshlrev_b32_e32 v16, 16, v38
	v_and_b32_e32 v17, 0xffff0000, v38
	v_pk_add_f32 v[60:61], v[12:13], v[16:17]
	v_lshlrev_b32_e32 v12, 16, v33
	s_waitcnt lgkmcnt(0)
	v_add_f32_e32 v26, v26, v32
	ds_bpermute_b32 v32, v84, v27
	v_and_b32_e32 v13, 0xffff0000, v33
	v_lshlrev_b32_e32 v16, 16, v39
	v_and_b32_e32 v17, 0xffff0000, v39
	v_pk_add_f32 v[58:59], v[12:13], v[16:17]
	v_add_f32_e32 v12, v60, v61
	v_add_f32_e32 v12, v58, v12
	v_add_f32_e32 v28, v59, v12
	v_lshlrev_b32_e32 v12, 16, v40
	v_and_b32_e32 v13, 0xffff0000, v40
	v_lshlrev_b32_e32 v16, 16, v46
	v_and_b32_e32 v17, 0xffff0000, v46
	s_waitcnt lgkmcnt(0)
	v_add_f32_e32 v27, v27, v32
	ds_bpermute_b32 v32, v84, v28
	v_pk_add_f32 v[44:45], v[12:13], v[16:17]
	v_lshlrev_b32_e32 v12, 16, v41
	v_and_b32_e32 v13, 0xffff0000, v41
	v_lshlrev_b32_e32 v16, 16, v47
	v_and_b32_e32 v17, 0xffff0000, v47
	v_pk_add_f32 v[46:47], v[12:13], v[16:17]
	v_add_f32_e32 v12, v44, v45
	v_add_f32_e32 v12, v46, v12
	v_add_f32_e32 v29, v47, v12
	v_lshlrev_b32_e32 v12, 16, v48
	v_and_b32_e32 v13, 0xffff0000, v48
	v_lshlrev_b32_e32 v16, 16, v50
	v_and_b32_e32 v17, 0xffff0000, v50
	s_waitcnt lgkmcnt(0)
	v_add_f32_e32 v28, v28, v32
	ds_bpermute_b32 v32, v84, v29
	v_pk_add_f32 v[40:41], v[12:13], v[16:17]
	v_lshlrev_b32_e32 v12, 16, v49
	v_and_b32_e32 v13, 0xffff0000, v49
	v_lshlrev_b32_e32 v16, 16, v51
	v_and_b32_e32 v17, 0xffff0000, v51
	v_pk_add_f32 v[38:39], v[12:13], v[16:17]
	v_add_f32_e32 v12, v40, v41
	v_add_f32_e32 v12, v38, v12
	v_add_f32_e32 v30, v39, v12
	v_lshlrev_b32_e32 v12, 16, v52
	v_and_b32_e32 v13, 0xffff0000, v52
	v_lshlrev_b32_e32 v16, 16, v54
	v_and_b32_e32 v17, 0xffff0000, v54
	s_waitcnt lgkmcnt(0)
	v_add_f32_e32 v29, v29, v32
	ds_bpermute_b32 v32, v84, v30
	v_pk_add_f32 v[22:23], v[12:13], v[16:17]
	v_lshlrev_b32_e32 v12, 16, v53
	v_and_b32_e32 v13, 0xffff0000, v53
	v_lshlrev_b32_e32 v16, 16, v55
	v_and_b32_e32 v17, 0xffff0000, v55
	v_pk_add_f32 v[24:25], v[12:13], v[16:17]
	v_add_f32_e32 v12, v22, v23
	v_add_f32_e32 v12, v24, v12
	v_add_f32_e32 v31, v25, v12
	v_lshlrev_b32_e32 v12, 16, v14
	v_and_b32_e32 v13, 0xffff0000, v14
	v_lshlrev_b32_e32 v16, 16, v68
	v_and_b32_e32 v17, 0xffff0000, v68
	s_waitcnt lgkmcnt(0)
	v_add_f32_e32 v30, v30, v32
	ds_bpermute_b32 v32, v84, v31
	v_pk_add_f32 v[16:17], v[12:13], v[16:17]
	v_lshlrev_b32_e32 v12, 16, v15
	v_and_b32_e32 v13, 0xffff0000, v15
	v_lshlrev_b32_e32 v14, 16, v69
	v_and_b32_e32 v15, 0xffff0000, v69
	v_pk_add_f32 v[14:15], v[12:13], v[14:15]
	v_add_f32_e32 v12, v16, v17
	v_add_f32_e32 v12, v14, v12
	v_add_f32_e32 v12, v15, v12
	ds_bpermute_b32 v13, v84, v70
	s_waitcnt lgkmcnt(1)
	v_add_f32_e32 v31, v31, v32
	ds_bpermute_b32 v32, v84, v12
	v_div_scale_f32 v101, s[0:1], v100, v100, v98
	s_waitcnt lgkmcnt(1)
	v_add_f32_e32 v13, v70, v13
	v_rcp_f32_e32 v102, v101
	s_waitcnt lgkmcnt(0)
	v_add_f32_e32 v12, v12, v32
	ds_bpermute_b32 v32, v85, v13
	v_fma_f32 v103, -v101, v102, 1.0
	v_fmac_f32_e32 v102, v103, v102
	v_div_scale_f32 v103, vcc, v98, v100, v98
	s_waitcnt lgkmcnt(0)
	v_add_f32_e32 v13, v13, v32
	ds_bpermute_b32 v32, v85, v26
	v_mul_f32_e32 v104, v103, v102
	v_fma_f32 v105, -v101, v104, v103
	v_fmac_f32_e32 v104, v105, v102
	v_fma_f32 v101, -v101, v104, v103
	s_waitcnt lgkmcnt(0)
	v_add_f32_e32 v26, v26, v32
	ds_bpermute_b32 v32, v85, v27
	v_div_fmas_f32 v101, v101, v102, v104
	v_div_fixup_f32 v98, v101, v100, v98
	v_mul_f32_e32 v100, 0xbfb8aa3b, v34
	v_exp_f32_e32 v100, v100
	s_waitcnt lgkmcnt(0)
	v_add_f32_e32 v27, v27, v32
	ds_bpermute_b32 v32, v85, v28
	v_add_f32_e32 v100, 1.0, v100
	v_div_scale_f32 v101, s[0:1], v100, v100, v34
	s_waitcnt lgkmcnt(0)
	v_add_f32_e32 v28, v28, v32
	ds_bpermute_b32 v32, v85, v29
	v_rcp_f32_e32 v102, v101
	s_waitcnt lgkmcnt(0)
	v_add_f32_e32 v29, v29, v32
	ds_bpermute_b32 v32, v85, v30
	v_fma_f32 v103, -v101, v102, 1.0
	v_fmac_f32_e32 v102, v103, v102
	v_div_scale_f32 v103, vcc, v34, v100, v34
	s_waitcnt lgkmcnt(0)
	v_add_f32_e32 v30, v30, v32
	ds_bpermute_b32 v32, v85, v31
	v_mul_f32_e32 v104, v103, v102
	v_fma_f32 v105, -v101, v104, v103
	v_fmac_f32_e32 v104, v105, v102
	v_fma_f32 v101, -v101, v104, v103
	s_waitcnt lgkmcnt(0)
	v_add_f32_e32 v31, v31, v32
	ds_bpermute_b32 v32, v85, v12
	v_div_fmas_f32 v101, v101, v102, v104
	v_div_fixup_f32 v100, v101, v100, v34
	v_mul_f32_e32 v34, 0xbfb8aa3b, v99
	v_exp_f32_e32 v34, v34
	s_waitcnt lgkmcnt(0)
	v_add_f32_e32 v12, v12, v32
	ds_bpermute_b32 v32, v86, v13
	v_add_f32_e32 v34, 1.0, v34
	v_div_scale_f32 v101, s[0:1], v34, v34, v99
	s_waitcnt lgkmcnt(0)
	v_add_f32_e32 v13, v13, v32
	ds_bpermute_b32 v32, v86, v26
	v_rcp_f32_e32 v102, v101
	s_waitcnt lgkmcnt(0)
	v_add_f32_e32 v26, v26, v32
	ds_bpermute_b32 v32, v86, v27
	v_fma_f32 v103, -v101, v102, 1.0
	v_fmac_f32_e32 v102, v103, v102
	v_div_scale_f32 v103, vcc, v99, v34, v99
	s_waitcnt lgkmcnt(0)
	v_add_f32_e32 v27, v27, v32
	ds_bpermute_b32 v32, v86, v28
	v_mul_f32_e32 v104, v103, v102
	v_fma_f32 v105, -v101, v104, v103
	v_fmac_f32_e32 v104, v105, v102
	v_fma_f32 v101, -v101, v104, v103
	s_waitcnt lgkmcnt(0)
	v_add_f32_e32 v28, v28, v32
	ds_bpermute_b32 v32, v86, v29
	v_div_fmas_f32 v101, v101, v102, v104
	v_div_fixup_f32 v99, v101, v34, v99
	v_mul_f32_e32 v34, 0xbfb8aa3b, v35
	v_exp_f32_e32 v34, v34
	s_waitcnt lgkmcnt(0)
	v_add_f32_e32 v29, v29, v32
	ds_bpermute_b32 v32, v86, v30
	v_add_f32_e32 v34, 1.0, v34
	v_div_scale_f32 v101, s[0:1], v34, v34, v35
	s_waitcnt lgkmcnt(0)
	v_add_f32_e32 v30, v30, v32
	ds_bpermute_b32 v32, v86, v31
	v_rcp_f32_e32 v102, v101
	s_waitcnt lgkmcnt(0)
	v_add_f32_e32 v31, v31, v32
	ds_bpermute_b32 v32, v86, v12
	v_fma_f32 v103, -v101, v102, 1.0
	v_fmac_f32_e32 v102, v103, v102
	v_div_scale_f32 v103, vcc, v35, v34, v35
	s_waitcnt lgkmcnt(0)
	v_add_f32_e32 v12, v12, v32
	ds_bpermute_b32 v32, v87, v13
	v_mul_f32_e32 v104, v103, v102
	v_fma_f32 v105, -v101, v104, v103
	v_fmac_f32_e32 v104, v105, v102
	v_fma_f32 v101, -v101, v104, v103
	s_waitcnt lgkmcnt(0)
	v_add_f32_e32 v13, v13, v32
	ds_bpermute_b32 v32, v87, v26
	v_div_fmas_f32 v101, v101, v102, v104
	v_div_fixup_f32 v101, v101, v34, v35
	s_waitcnt lgkmcnt(0)
	v_add_f32_e32 v26, v26, v32
	ds_bpermute_b32 v32, v87, v27
	s_waitcnt lgkmcnt(0)
	v_add_f32_e32 v27, v27, v32
	ds_bpermute_b32 v32, v87, v28
	s_waitcnt lgkmcnt(0)
	v_add_f32_e32 v28, v28, v32
	ds_bpermute_b32 v32, v87, v29
	s_waitcnt lgkmcnt(0)
	v_add_f32_e32 v29, v29, v32
	ds_bpermute_b32 v32, v87, v30
	s_waitcnt lgkmcnt(0)
	v_add_f32_e32 v30, v30, v32
	ds_bpermute_b32 v32, v87, v31
	s_waitcnt lgkmcnt(0)
	v_add_f32_e32 v31, v31, v32
	ds_bpermute_b32 v32, v87, v12
	s_waitcnt lgkmcnt(0)
	v_add_f32_e32 v12, v12, v32
	ds_bpermute_b32 v32, v88, v13
	s_waitcnt lgkmcnt(0)
	v_add_f32_e32 v13, v13, v32
	ds_bpermute_b32 v32, v88, v26
	s_waitcnt lgkmcnt(0)
	v_add_f32_e32 v26, v26, v32
	ds_bpermute_b32 v32, v88, v27
	s_waitcnt lgkmcnt(0)
	v_add_f32_e32 v27, v27, v32
	ds_bpermute_b32 v32, v88, v28
	s_waitcnt lgkmcnt(0)
	v_add_f32_e32 v28, v28, v32
	ds_bpermute_b32 v32, v88, v29
	s_waitcnt lgkmcnt(0)
	v_add_f32_e32 v29, v29, v32
	ds_bpermute_b32 v32, v88, v30
	s_waitcnt lgkmcnt(0)
	v_add_f32_e32 v30, v30, v32
	ds_bpermute_b32 v32, v88, v31
	s_waitcnt lgkmcnt(0)
	v_add_f32_e32 v31, v31, v32
	ds_bpermute_b32 v32, v88, v12
	s_waitcnt lgkmcnt(0)
	v_add_f32_e32 v12, v12, v32
	ds_bpermute_b32 v32, v89, v13
	s_waitcnt lgkmcnt(0)
	v_add_f32_e32 v13, v13, v32
	ds_bpermute_b32 v32, v89, v26
	v_fmamk_f32 v5, v13, 0xbb800000, v5
	v_fmac_f32_e32 v4, 0xbb800000, v13
	v_fmamk_f32 v7, v13, 0xbb800000, v7
	v_fmac_f32_e32 v6, 0xbb800000, v13
	s_waitcnt lgkmcnt(0)
	v_add_f32_e32 v26, v26, v32
	v_fmamk_f32 v81, v26, 0xbb800000, v81
	v_fmac_f32_e32 v80, 0xbb800000, v26
	v_pk_mul_f32 v[92:93], v[4:5], v[4:5]
	v_fmamk_f32 v79, v26, 0xbb800000, v79
	v_fmac_f32_e32 v78, 0xbb800000, v26
	v_pk_mul_f32 v[96:97], v[80:81], v[80:81]
	v_pk_mul_f32 v[90:91], v[6:7], v[6:7]
	v_pk_mul_f32 v[94:95], v[78:79], v[78:79]
	v_mov_b32_e32 v34, v96
	v_mov_b32_e32 v35, v92
	v_mov_b32_e32 v92, v97
	v_pk_add_f32 v[34:35], v[34:35], v[92:93]
	v_mov_b32_e32 v92, v94
	v_mov_b32_e32 v93, v90
	v_pk_add_f32 v[34:35], v[92:93], v[34:35]
	v_mov_b32_e32 v90, v95
	v_pk_add_f32 v[34:35], v[90:91], v[34:35]
	ds_bpermute_b32 v91, v84, v35
	ds_bpermute_b32 v90, v84, v34
	ds_bpermute_b32 v32, v89, v27
	s_waitcnt lgkmcnt(1)
	v_pk_add_f32 v[34:35], v[34:35], v[90:91]
	ds_bpermute_b32 v91, v85, v35
	ds_bpermute_b32 v90, v85, v34
	s_waitcnt lgkmcnt(2)
	v_add_f32_e32 v27, v27, v32
	ds_bpermute_b32 v32, v89, v28
	v_fmamk_f32 v65, v27, 0xbb800000, v65
	v_fmac_f32_e32 v64, 0xbb800000, v27
	s_waitcnt lgkmcnt(1)
	v_pk_add_f32 v[34:35], v[34:35], v[90:91]
	ds_bpermute_b32 v91, v86, v35
	s_waitcnt lgkmcnt(1)
	v_add_f32_e32 v28, v28, v32
	ds_bpermute_b32 v32, v89, v29
	ds_bpermute_b32 v90, v86, v34
	v_fmamk_f32 v61, v28, 0xbb800000, v61
	v_fmac_f32_e32 v60, 0xbb800000, v28
	v_fmamk_f32 v67, v27, 0xbb800000, v67
	s_waitcnt lgkmcnt(1)
	v_add_f32_e32 v29, v29, v32
	ds_bpermute_b32 v32, v89, v30
	s_waitcnt lgkmcnt(1)
	v_pk_add_f32 v[34:35], v[34:35], v[90:91]
	ds_bpermute_b32 v91, v87, v35
	ds_bpermute_b32 v90, v87, v34
	v_fmac_f32_e32 v66, 0xbb800000, v27
	s_waitcnt lgkmcnt(2)
	v_add_f32_e32 v30, v30, v32
	ds_bpermute_b32 v32, v89, v31
	v_pk_mul_f32 v[70:71], v[64:65], v[64:65]
	s_waitcnt lgkmcnt(1)
	v_pk_add_f32 v[34:35], v[34:35], v[90:91]
	ds_bpermute_b32 v91, v88, v35
	ds_bpermute_b32 v90, v88, v34
	s_waitcnt lgkmcnt(2)
	v_add_f32_e32 v31, v31, v32
	ds_bpermute_b32 v32, v89, v12
	v_fmamk_f32 v59, v28, 0xbb800000, v59
	v_fmac_f32_e32 v58, 0xbb800000, v28
	s_waitcnt lgkmcnt(1)
	v_pk_add_f32 v[34:35], v[34:35], v[90:91]
	ds_bpermute_b32 v91, v89, v35
	ds_bpermute_b32 v90, v89, v34
	s_waitcnt lgkmcnt(2)
	v_add_f32_e32 v12, v12, v32
	v_fmamk_f32 v17, v12, 0xbb800000, v17
	v_fmac_f32_e32 v16, 0xbb800000, v12
	v_fmamk_f32 v15, v12, 0xbb800000, v15
	v_fmac_f32_e32 v14, 0xbb800000, v12
	v_mad_i64_i32 v[12:13], s[0:1], v82, s70, v[10:11]
	s_mov_b32 s0, 0x358637bd
	s_waitcnt lgkmcnt(0)
	v_pk_add_f32 v[90:91], v[34:35], v[90:91]
	v_mov_b64_e32 v[34:35], s[0:1]
	v_pk_fma_f32 v[90:91], v[90:91], s[34:35], v[34:35] op_sel_hi:[1,0,0]
	v_pk_mul_f32 v[74:75], v[60:61], v[60:61]
	v_mul_f32_e32 v92, 0x4b800000, v91
	v_cmp_gt_f32_e64 s[0:1], s72, v91
	v_cmp_gt_f32_e32 vcc, s72, v90
	v_pk_mul_f32 v[68:69], v[66:67], v[66:67]
	v_cndmask_b32_e64 v91, v91, v92, s[0:1]
	v_rsq_f32_e32 v91, v91
	v_pk_mul_f32 v[72:73], v[58:59], v[58:59]
	v_fmamk_f32 v45, v29, 0xbb800000, v45
	v_fmac_f32_e32 v44, 0xbb800000, v29
	v_mul_f32_e32 v92, 0x45800000, v91
	v_cndmask_b32_e64 v91, v91, v92, s[0:1]
	v_mul_f32_e32 v4, v4, v91
	v_mul_f32_e32 v5, v5, v91
	v_mul_f32_e32 v4, v0, v4
	v_mul_f32_e32 v5, v1, v5
	v_mul_f32_e32 v4, v98, v4
	v_mul_f32_e32 v5, v100, v5
	v_cvt_pk_bf16_f32 v4, v4, v5
	v_mul_f32_e32 v5, v6, v91
	v_mul_f32_e32 v5, v2, v5
	v_mul_f32_e32 v6, v7, v91
	v_mul_f32_e32 v5, v99, v5
	v_mul_f32_e32 v6, v3, v6
	v_mul_f32_e32 v6, v101, v6
	v_cvt_pk_bf16_f32 v5, v5, v6
	global_store_dwordx2 v[12:13], v[4:5], off
	v_mul_f32_e32 v4, 0x4b800000, v90
	v_cndmask_b32_e32 v4, v90, v4, vcc
	v_rsq_f32_e32 v4, v4
	v_lshlrev_b32_e32 v91, 16, v76
	v_and_b32_e32 v76, 0xffff0000, v76
	v_lshlrev_b32_e32 v92, 16, v77
	v_mul_f32_e32 v5, 0x45800000, v4
	v_cndmask_b32_e32 v90, v4, v5, vcc
	ds_read_b128 v[4:7], v83 offset:1024
	v_mul_f32_e32 v80, v80, v90
	v_and_b32_e32 v77, 0xffff0000, v77
	v_fmamk_f32 v41, v30, 0xbb800000, v41
	v_fmac_f32_e32 v40, 0xbb800000, v30
	s_waitcnt lgkmcnt(0)
	v_mul_f32_e32 v4, v80, v4
	v_mul_f32_e32 v80, 0xbfb8aa3b, v91
	v_exp_f32_e32 v80, v80
	v_fmamk_f32 v47, v29, 0xbb800000, v47
	v_fmac_f32_e32 v46, 0xbb800000, v29
	v_pk_mul_f32 v[50:51], v[44:45], v[44:45]
	v_add_f32_e32 v80, 1.0, v80
	v_div_scale_f32 v93, s[0:1], v80, v80, v91
	v_rcp_f32_e32 v94, v93
	v_fmamk_f32 v39, v30, 0xbb800000, v39
	v_fmac_f32_e32 v38, 0xbb800000, v30
	v_pk_mul_f32 v[54:55], v[40:41], v[40:41]
	v_fma_f32 v95, -v93, v94, 1.0
	v_fmac_f32_e32 v94, v95, v94
	v_div_scale_f32 v95, vcc, v91, v80, v91
	v_mul_f32_e32 v96, v95, v94
	v_fma_f32 v97, -v93, v96, v95
	v_fmac_f32_e32 v96, v97, v94
	v_fma_f32 v93, -v93, v96, v95
	v_div_fmas_f32 v93, v93, v94, v96
	v_div_fixup_f32 v80, v93, v80, v91
	v_mul_f32_e32 v4, v80, v4
	v_mul_f32_e32 v80, v81, v90
	v_mul_f32_e32 v5, v80, v5
	v_mul_f32_e32 v80, 0xbfb8aa3b, v76
	v_exp_f32_e32 v80, v80
	v_pk_mul_f32 v[48:49], v[46:47], v[46:47]
	v_pk_mul_f32 v[52:53], v[38:39], v[38:39]
	v_fmamk_f32 v23, v31, 0xbb800000, v23
	v_add_f32_e32 v80, 1.0, v80
	v_div_scale_f32 v81, s[0:1], v80, v80, v76
	v_rcp_f32_e32 v91, v81
	v_fmac_f32_e32 v22, 0xbb800000, v31
	v_fmamk_f32 v25, v31, 0xbb800000, v25
	v_fmac_f32_e32 v24, 0xbb800000, v31
	v_fma_f32 v93, -v81, v91, 1.0
	v_fmac_f32_e32 v91, v93, v91
	v_div_scale_f32 v93, vcc, v76, v80, v76
	v_mul_f32_e32 v94, v93, v91
	v_fma_f32 v95, -v81, v94, v93
	v_fmac_f32_e32 v94, v95, v91
	v_fma_f32 v81, -v81, v94, v93
	v_div_fmas_f32 v81, v81, v91, v94
	v_div_fixup_f32 v76, v81, v80, v76
	v_mul_f32_e32 v5, v76, v5
	v_cvt_pk_bf16_f32 v4, v4, v5
	v_mul_f32_e32 v5, v78, v90
	v_mul_f32_e32 v5, v5, v6
	v_mul_f32_e32 v6, 0xbfb8aa3b, v92
	v_exp_f32_e32 v6, v6
	v_pk_mul_f32 v[28:29], v[22:23], v[22:23]
	v_pk_mul_f32 v[32:33], v[16:17], v[16:17]
	v_pk_mul_f32 v[26:27], v[24:25], v[24:25]
	v_add_f32_e32 v6, 1.0, v6
	v_div_scale_f32 v76, s[0:1], v6, v6, v92
	v_rcp_f32_e32 v78, v76
	v_pk_mul_f32 v[30:31], v[14:15], v[14:15]
	v_add_u32_e32 v82, s14, v82
	v_fma_f32 v80, -v76, v78, 1.0
	v_fmac_f32_e32 v78, v80, v78
	v_div_scale_f32 v80, vcc, v92, v6, v92
	v_mul_f32_e32 v81, v80, v78
	v_fma_f32 v91, -v76, v81, v80
	v_fmac_f32_e32 v81, v91, v78
	v_fma_f32 v76, -v76, v81, v80
	v_div_fmas_f32 v76, v76, v78, v81
	v_div_fixup_f32 v6, v76, v6, v92
	v_mul_f32_e32 v5, v6, v5
	v_mul_f32_e32 v6, v79, v90
	v_mul_f32_e32 v6, v6, v7
	v_mul_f32_e32 v7, 0xbfb8aa3b, v77
	v_exp_f32_e32 v7, v7
	s_nop 0
	v_add_f32_e32 v7, 1.0, v7
	v_div_scale_f32 v76, s[0:1], v7, v7, v77
	v_rcp_f32_e32 v78, v76
	s_nop 0
	v_fma_f32 v79, -v76, v78, 1.0
	v_fmac_f32_e32 v78, v79, v78
	v_div_scale_f32 v79, vcc, v77, v7, v77
	v_mul_f32_e32 v80, v79, v78
	v_fma_f32 v81, -v76, v80, v79
	v_fmac_f32_e32 v80, v81, v78
	v_fma_f32 v76, -v76, v80, v79
	v_div_fmas_f32 v76, v76, v78, v80
	v_div_fixup_f32 v7, v76, v7, v77
	v_lshlrev_b32_e32 v76, 16, v62
	v_mul_f32_e32 v78, 0xbfb8aa3b, v76
	v_exp_f32_e32 v78, v78
	v_and_b32_e32 v62, 0xffff0000, v62
	v_lshlrev_b32_e32 v77, 16, v63
	v_and_b32_e32 v63, 0xffff0000, v63
	v_add_f32_e32 v78, 1.0, v78
	v_div_scale_f32 v79, s[0:1], v78, v78, v76
	v_rcp_f32_e32 v80, v79
	v_mul_f32_e32 v6, v7, v6
	v_cvt_pk_bf16_f32 v5, v5, v6
	global_store_dwordx2 v[12:13], v[4:5], off offset:512
	v_fma_f32 v81, -v79, v80, 1.0
	v_fmac_f32_e32 v80, v81, v80
	v_div_scale_f32 v81, vcc, v76, v78, v76
	v_mul_f32_e32 v90, v81, v80
	v_fma_f32 v91, -v79, v90, v81
	v_fmac_f32_e32 v90, v91, v80
	v_fma_f32 v79, -v79, v90, v81
	v_div_fmas_f32 v79, v79, v80, v90
	v_div_fixup_f32 v76, v79, v78, v76
	v_mul_f32_e32 v78, 0xbfb8aa3b, v62
	v_exp_f32_e32 v78, v78
	ds_read_b128 v[4:7], v83 offset:2048
	v_add_f32_e32 v78, 1.0, v78
	v_div_scale_f32 v79, s[0:1], v78, v78, v62
	v_rcp_f32_e32 v80, v79
	s_nop 0
	v_fma_f32 v81, -v79, v80, 1.0
	v_fmac_f32_e32 v80, v81, v80
	v_div_scale_f32 v81, vcc, v62, v78, v62
	v_mul_f32_e32 v90, v81, v80
	v_fma_f32 v91, -v79, v90, v81
	v_fmac_f32_e32 v90, v91, v80
	v_fma_f32 v79, -v79, v90, v81
	v_div_fmas_f32 v79, v79, v80, v90
	v_div_fixup_f32 v78, v79, v78, v62
	v_mul_f32_e32 v62, 0xbfb8aa3b, v77
	v_exp_f32_e32 v62, v62
	s_nop 0
	v_add_f32_e32 v62, 1.0, v62
	v_div_scale_f32 v79, s[0:1], v62, v62, v77
	v_rcp_f32_e32 v80, v79
	s_nop 0
	v_fma_f32 v81, -v79, v80, 1.0
	v_fmac_f32_e32 v80, v81, v80
	v_div_scale_f32 v81, vcc, v77, v62, v77
	v_mul_f32_e32 v90, v81, v80
	v_fma_f32 v91, -v79, v90, v81
	v_fmac_f32_e32 v90, v91, v80
	v_fma_f32 v79, -v79, v90, v81
	v_div_fmas_f32 v79, v79, v80, v90
	v_div_fixup_f32 v77, v79, v62, v77
	v_mul_f32_e32 v62, 0xbfb8aa3b, v63
	v_exp_f32_e32 v62, v62
	s_nop 0
	v_add_f32_e32 v62, 1.0, v62
	v_div_scale_f32 v79, s[0:1], v62, v62, v63
	v_rcp_f32_e32 v80, v79
	s_nop 0
	v_fma_f32 v81, -v79, v80, 1.0
	v_fmac_f32_e32 v80, v81, v80
	v_div_scale_f32 v81, vcc, v63, v62, v63
	v_mul_f32_e32 v90, v81, v80
	v_fma_f32 v91, -v79, v90, v81
	v_fmac_f32_e32 v90, v91, v80
	v_fma_f32 v79, -v79, v90, v81
	v_div_fmas_f32 v79, v79, v80, v90
	v_div_fixup_f32 v79, v79, v62, v63
	v_mov_b32_e32 v62, v74
	v_mov_b32_e32 v63, v70
	v_mov_b32_e32 v70, v75
	v_pk_add_f32 v[62:63], v[62:63], v[70:71]
	v_mov_b32_e32 v70, v72
	v_mov_b32_e32 v71, v68
	v_pk_add_f32 v[62:63], v[70:71], v[62:63]
	v_mov_b32_e32 v68, v73
	v_pk_add_f32 v[62:63], v[68:69], v[62:63]
	ds_bpermute_b32 v69, v84, v63
	ds_bpermute_b32 v68, v84, v62
	s_waitcnt lgkmcnt(0)
	v_pk_add_f32 v[62:63], v[62:63], v[68:69]
	ds_bpermute_b32 v69, v85, v63
	ds_bpermute_b32 v68, v85, v62
	s_waitcnt lgkmcnt(0)
	v_pk_add_f32 v[62:63], v[62:63], v[68:69]
	ds_bpermute_b32 v69, v86, v63
	ds_bpermute_b32 v68, v86, v62
	s_waitcnt lgkmcnt(0)
	v_pk_add_f32 v[62:63], v[62:63], v[68:69]
	ds_bpermute_b32 v69, v87, v63
	ds_bpermute_b32 v68, v87, v62
	s_waitcnt lgkmcnt(0)
	v_pk_add_f32 v[62:63], v[62:63], v[68:69]
	ds_bpermute_b32 v69, v88, v63
	ds_bpermute_b32 v68, v88, v62
	s_waitcnt lgkmcnt(0)
	v_pk_add_f32 v[62:63], v[62:63], v[68:69]
	ds_bpermute_b32 v69, v89, v63
	ds_bpermute_b32 v68, v89, v62
	s_waitcnt lgkmcnt(0)
	v_pk_add_f32 v[62:63], v[62:63], v[68:69]
	s_nop 0
	v_pk_fma_f32 v[62:63], v[62:63], s[34:35], v[34:35] op_sel_hi:[1,0,0]
	s_nop 0
	v_mul_f32_e32 v68, 0x4b800000, v63
	v_cmp_gt_f32_e64 s[0:1], s72, v63
	v_cmp_gt_f32_e32 vcc, s72, v62
	s_nop 0
	v_cndmask_b32_e64 v63, v63, v68, s[0:1]
	v_rsq_f32_e32 v63, v63
	s_nop 0
	v_mul_f32_e32 v68, 0x45800000, v63
	v_cndmask_b32_e64 v63, v63, v68, s[0:1]
	v_mul_f32_e32 v64, v64, v63
	v_mul_f32_e32 v4, v64, v4
	v_mul_f32_e32 v64, v65, v63
	v_mul_f32_e32 v5, v64, v5
	v_mul_f32_e32 v4, v76, v4
	v_mul_f32_e32 v5, v78, v5
	v_cvt_pk_bf16_f32 v4, v4, v5
	v_mul_f32_e32 v5, v66, v63
	v_mul_f32_e32 v5, v5, v6
	v_mul_f32_e32 v6, v67, v63
	v_mul_f32_e32 v5, v77, v5
	v_mul_f32_e32 v6, v6, v7
	v_mul_f32_e32 v6, v79, v6
	v_cvt_pk_bf16_f32 v5, v5, v6
	global_store_dwordx2 v[12:13], v[4:5], off offset:1024
	v_mul_f32_e32 v4, 0x4b800000, v62
	v_cndmask_b32_e32 v4, v62, v4, vcc
	v_rsq_f32_e32 v4, v4
	v_lshlrev_b32_e32 v63, 16, v56
	v_and_b32_e32 v56, 0xffff0000, v56
	v_lshlrev_b32_e32 v64, 16, v57
	v_mul_f32_e32 v5, 0x45800000, v4
	v_cndmask_b32_e32 v62, v4, v5, vcc
	ds_read_b128 v[4:7], v83 offset:3072
	v_mul_f32_e32 v60, v60, v62
	v_and_b32_e32 v57, 0xffff0000, v57
	s_waitcnt lgkmcnt(0)
	v_mul_f32_e32 v4, v60, v4
	v_mul_f32_e32 v60, 0xbfb8aa3b, v63
	v_exp_f32_e32 v60, v60
	s_nop 0
	v_add_f32_e32 v60, 1.0, v60
	v_div_scale_f32 v65, s[0:1], v60, v60, v63
	v_rcp_f32_e32 v66, v65
	s_nop 0
	v_fma_f32 v67, -v65, v66, 1.0
	v_fmac_f32_e32 v66, v67, v66
	v_div_scale_f32 v67, vcc, v63, v60, v63
	v_mul_f32_e32 v68, v67, v66
	v_fma_f32 v69, -v65, v68, v67
	v_fmac_f32_e32 v68, v69, v66
	v_fma_f32 v65, -v65, v68, v67
	v_div_fmas_f32 v65, v65, v66, v68
	v_div_fixup_f32 v60, v65, v60, v63
	v_mul_f32_e32 v4, v60, v4
	v_mul_f32_e32 v60, v61, v62
	v_mul_f32_e32 v5, v60, v5
	v_mul_f32_e32 v60, 0xbfb8aa3b, v56
	v_exp_f32_e32 v60, v60
	s_nop 0
	v_add_f32_e32 v60, 1.0, v60
	v_div_scale_f32 v61, s[0:1], v60, v60, v56
	v_rcp_f32_e32 v63, v61
	s_nop 0
	v_fma_f32 v65, -v61, v63, 1.0
	v_fmac_f32_e32 v63, v65, v63
	v_div_scale_f32 v65, vcc, v56, v60, v56
	v_mul_f32_e32 v66, v65, v63
	v_fma_f32 v67, -v61, v66, v65
	v_fmac_f32_e32 v66, v67, v63
	v_fma_f32 v61, -v61, v66, v65
	v_div_fmas_f32 v61, v61, v63, v66
	v_div_fixup_f32 v56, v61, v60, v56
	v_mul_f32_e32 v5, v56, v5
	v_cvt_pk_bf16_f32 v4, v4, v5
	v_mul_f32_e32 v5, v58, v62
	v_mul_f32_e32 v5, v5, v6
	v_mul_f32_e32 v6, 0xbfb8aa3b, v64
	v_exp_f32_e32 v6, v6
	s_nop 0
	v_add_f32_e32 v6, 1.0, v6
	v_div_scale_f32 v56, s[0:1], v6, v6, v64
	v_rcp_f32_e32 v58, v56
	s_nop 0
	v_fma_f32 v60, -v56, v58, 1.0
	v_fmac_f32_e32 v58, v60, v58
	v_div_scale_f32 v60, vcc, v64, v6, v64
	v_mul_f32_e32 v61, v60, v58
	v_fma_f32 v63, -v56, v61, v60
	v_fmac_f32_e32 v61, v63, v58
	v_fma_f32 v56, -v56, v61, v60
	v_div_fmas_f32 v56, v56, v58, v61
	v_div_fixup_f32 v6, v56, v6, v64
	v_mul_f32_e32 v5, v6, v5
	v_mul_f32_e32 v6, v59, v62
	v_mul_f32_e32 v6, v6, v7
	v_mul_f32_e32 v7, 0xbfb8aa3b, v57
	v_exp_f32_e32 v7, v7
	s_nop 0
	v_add_f32_e32 v7, 1.0, v7
	v_div_scale_f32 v56, s[0:1], v7, v7, v57
	v_rcp_f32_e32 v58, v56
	s_nop 0
	v_fma_f32 v59, -v56, v58, 1.0
	v_fmac_f32_e32 v58, v59, v58
	v_div_scale_f32 v59, vcc, v57, v7, v57
	v_mul_f32_e32 v60, v59, v58
	v_fma_f32 v61, -v56, v60, v59
	v_fmac_f32_e32 v60, v61, v58
	v_fma_f32 v56, -v56, v60, v59
	v_div_fmas_f32 v56, v56, v58, v60
	v_div_fixup_f32 v7, v56, v7, v57
	v_lshlrev_b32_e32 v56, 16, v42
	v_mul_f32_e32 v58, 0xbfb8aa3b, v56
	v_exp_f32_e32 v58, v58
	v_and_b32_e32 v42, 0xffff0000, v42
	v_lshlrev_b32_e32 v57, 16, v43
	v_and_b32_e32 v43, 0xffff0000, v43
	v_add_f32_e32 v58, 1.0, v58
	v_div_scale_f32 v59, s[0:1], v58, v58, v56
	v_rcp_f32_e32 v60, v59
	v_mul_f32_e32 v6, v7, v6
	v_cvt_pk_bf16_f32 v5, v5, v6
	global_store_dwordx2 v[12:13], v[4:5], off offset:1536
	v_fma_f32 v61, -v59, v60, 1.0
	v_fmac_f32_e32 v60, v61, v60
	v_div_scale_f32 v61, vcc, v56, v58, v56
	v_mul_f32_e32 v62, v61, v60
	v_fma_f32 v63, -v59, v62, v61
	v_fmac_f32_e32 v62, v63, v60
	v_fma_f32 v59, -v59, v62, v61
	v_div_fmas_f32 v59, v59, v60, v62
	v_div_fixup_f32 v56, v59, v58, v56
	v_mul_f32_e32 v58, 0xbfb8aa3b, v42
	v_exp_f32_e32 v58, v58
	ds_read_b128 v[4:7], v83 offset:4096
	v_add_f32_e32 v58, 1.0, v58
	v_div_scale_f32 v59, s[0:1], v58, v58, v42
	v_rcp_f32_e32 v60, v59
	s_nop 0
	v_fma_f32 v61, -v59, v60, 1.0
	v_fmac_f32_e32 v60, v61, v60
	v_div_scale_f32 v61, vcc, v42, v58, v42
	v_mul_f32_e32 v62, v61, v60
	v_fma_f32 v63, -v59, v62, v61
	v_fmac_f32_e32 v62, v63, v60
	v_fma_f32 v59, -v59, v62, v61
	v_div_fmas_f32 v59, v59, v60, v62
	v_div_fixup_f32 v58, v59, v58, v42
	v_mul_f32_e32 v42, 0xbfb8aa3b, v57
	v_exp_f32_e32 v42, v42
	s_nop 0
	v_add_f32_e32 v42, 1.0, v42
	v_div_scale_f32 v59, s[0:1], v42, v42, v57
	v_rcp_f32_e32 v60, v59
	s_nop 0
	v_fma_f32 v61, -v59, v60, 1.0
	v_fmac_f32_e32 v60, v61, v60
	v_div_scale_f32 v61, vcc, v57, v42, v57
	v_mul_f32_e32 v62, v61, v60
	v_fma_f32 v63, -v59, v62, v61
	v_fmac_f32_e32 v62, v63, v60
	v_fma_f32 v59, -v59, v62, v61
	v_div_fmas_f32 v59, v59, v60, v62
	v_div_fixup_f32 v57, v59, v42, v57
	v_mul_f32_e32 v42, 0xbfb8aa3b, v43
	v_exp_f32_e32 v42, v42
	s_nop 0
	v_add_f32_e32 v42, 1.0, v42
	v_div_scale_f32 v59, s[0:1], v42, v42, v43
	v_rcp_f32_e32 v60, v59
	s_nop 0
	v_fma_f32 v61, -v59, v60, 1.0
	v_fmac_f32_e32 v60, v61, v60
	v_div_scale_f32 v61, vcc, v43, v42, v43
	v_mul_f32_e32 v62, v61, v60
	v_fma_f32 v63, -v59, v62, v61
	v_fmac_f32_e32 v62, v63, v60
	v_fma_f32 v59, -v59, v62, v61
	v_div_fmas_f32 v59, v59, v60, v62
	v_div_fixup_f32 v59, v59, v42, v43
	v_mov_b32_e32 v42, v54
	v_mov_b32_e32 v43, v50
	v_mov_b32_e32 v50, v55
	v_pk_add_f32 v[42:43], v[42:43], v[50:51]
	v_mov_b32_e32 v50, v52
	v_mov_b32_e32 v51, v48
	v_pk_add_f32 v[42:43], v[50:51], v[42:43]
	v_mov_b32_e32 v48, v53
	v_pk_add_f32 v[42:43], v[48:49], v[42:43]
	ds_bpermute_b32 v49, v84, v43
	ds_bpermute_b32 v48, v84, v42
	s_waitcnt lgkmcnt(0)
	v_pk_add_f32 v[42:43], v[42:43], v[48:49]
	ds_bpermute_b32 v49, v85, v43
	ds_bpermute_b32 v48, v85, v42
	s_waitcnt lgkmcnt(0)
	v_pk_add_f32 v[42:43], v[42:43], v[48:49]
	ds_bpermute_b32 v49, v86, v43
	ds_bpermute_b32 v48, v86, v42
	s_waitcnt lgkmcnt(0)
	v_pk_add_f32 v[42:43], v[42:43], v[48:49]
	ds_bpermute_b32 v49, v87, v43
	ds_bpermute_b32 v48, v87, v42
	s_waitcnt lgkmcnt(0)
	v_pk_add_f32 v[42:43], v[42:43], v[48:49]
	ds_bpermute_b32 v49, v88, v43
	ds_bpermute_b32 v48, v88, v42
	s_waitcnt lgkmcnt(0)
	v_pk_add_f32 v[42:43], v[42:43], v[48:49]
	ds_bpermute_b32 v49, v89, v43
	ds_bpermute_b32 v48, v89, v42
	s_waitcnt lgkmcnt(0)
	v_pk_add_f32 v[42:43], v[42:43], v[48:49]
	s_nop 0
	v_pk_fma_f32 v[42:43], v[42:43], s[34:35], v[34:35] op_sel_hi:[1,0,0]
	s_nop 0
	v_mul_f32_e32 v48, 0x4b800000, v43
	v_cmp_gt_f32_e64 s[0:1], s72, v43
	v_cmp_gt_f32_e32 vcc, s72, v42
	s_nop 0
	v_cndmask_b32_e64 v43, v43, v48, s[0:1]
	v_rsq_f32_e32 v43, v43
	s_nop 0
	v_mul_f32_e32 v48, 0x45800000, v43
	v_cndmask_b32_e64 v43, v43, v48, s[0:1]
	v_mul_f32_e32 v44, v44, v43
	v_mul_f32_e32 v4, v44, v4
	v_mul_f32_e32 v44, v45, v43
	v_mul_f32_e32 v5, v44, v5
	v_mul_f32_e32 v4, v56, v4
	v_mul_f32_e32 v5, v58, v5
	v_cvt_pk_bf16_f32 v4, v4, v5
	v_mul_f32_e32 v5, v46, v43
	v_mul_f32_e32 v5, v5, v6
	v_mul_f32_e32 v6, v47, v43
	v_mul_f32_e32 v5, v57, v5
	v_mul_f32_e32 v6, v6, v7
	v_mul_f32_e32 v6, v59, v6
	v_cvt_pk_bf16_f32 v5, v5, v6
	global_store_dwordx2 v[12:13], v[4:5], off offset:2048
	v_mul_f32_e32 v4, 0x4b800000, v42
	v_cndmask_b32_e32 v4, v42, v4, vcc
	v_rsq_f32_e32 v4, v4
	v_lshlrev_b32_e32 v43, 16, v36
	v_and_b32_e32 v36, 0xffff0000, v36
	v_lshlrev_b32_e32 v44, 16, v37
	v_mul_f32_e32 v5, 0x45800000, v4
	v_cndmask_b32_e32 v42, v4, v5, vcc
	ds_read_b128 v[4:7], v83 offset:5120
	v_mul_f32_e32 v40, v40, v42
	v_and_b32_e32 v37, 0xffff0000, v37
	s_waitcnt lgkmcnt(0)
	v_mul_f32_e32 v4, v40, v4
	v_mul_f32_e32 v40, 0xbfb8aa3b, v43
	v_exp_f32_e32 v40, v40
	s_nop 0
	v_add_f32_e32 v40, 1.0, v40
	v_div_scale_f32 v45, s[0:1], v40, v40, v43
	v_rcp_f32_e32 v46, v45
	s_nop 0
	v_fma_f32 v47, -v45, v46, 1.0
	v_fmac_f32_e32 v46, v47, v46
	v_div_scale_f32 v47, vcc, v43, v40, v43
	v_mul_f32_e32 v48, v47, v46
	v_fma_f32 v49, -v45, v48, v47
	v_fmac_f32_e32 v48, v49, v46
	v_fma_f32 v45, -v45, v48, v47
	v_div_fmas_f32 v45, v45, v46, v48
	v_div_fixup_f32 v40, v45, v40, v43
	v_mul_f32_e32 v4, v40, v4
	v_mul_f32_e32 v40, v41, v42
	v_mul_f32_e32 v5, v40, v5
	v_mul_f32_e32 v40, 0xbfb8aa3b, v36
	v_exp_f32_e32 v40, v40
	s_nop 0
	v_add_f32_e32 v40, 1.0, v40
	v_div_scale_f32 v41, s[0:1], v40, v40, v36
	v_rcp_f32_e32 v43, v41
	s_nop 0
	v_fma_f32 v45, -v41, v43, 1.0
	v_fmac_f32_e32 v43, v45, v43
	v_div_scale_f32 v45, vcc, v36, v40, v36
	v_mul_f32_e32 v46, v45, v43
	v_fma_f32 v47, -v41, v46, v45
	v_fmac_f32_e32 v46, v47, v43
	v_fma_f32 v41, -v41, v46, v45
	v_div_fmas_f32 v41, v41, v43, v46
	v_div_fixup_f32 v36, v41, v40, v36
	v_mul_f32_e32 v5, v36, v5
	v_cvt_pk_bf16_f32 v4, v4, v5
	v_mul_f32_e32 v5, v38, v42
	v_mul_f32_e32 v5, v5, v6
	v_mul_f32_e32 v6, 0xbfb8aa3b, v44
	v_exp_f32_e32 v6, v6
	s_nop 0
	v_add_f32_e32 v6, 1.0, v6
	v_div_scale_f32 v36, s[0:1], v6, v6, v44
	v_rcp_f32_e32 v38, v36
	s_nop 0
	v_fma_f32 v40, -v36, v38, 1.0
	v_fmac_f32_e32 v38, v40, v38
	v_div_scale_f32 v40, vcc, v44, v6, v44
	v_mul_f32_e32 v41, v40, v38
	v_fma_f32 v43, -v36, v41, v40
	v_fmac_f32_e32 v41, v43, v38
	v_fma_f32 v36, -v36, v41, v40
	v_div_fmas_f32 v36, v36, v38, v41
	v_div_fixup_f32 v6, v36, v6, v44
	v_mul_f32_e32 v5, v6, v5
	v_mul_f32_e32 v6, v39, v42
	v_mul_f32_e32 v6, v6, v7
	v_mul_f32_e32 v7, 0xbfb8aa3b, v37
	v_exp_f32_e32 v7, v7
	s_nop 0
	v_add_f32_e32 v7, 1.0, v7
	v_div_scale_f32 v36, s[0:1], v7, v7, v37
	v_rcp_f32_e32 v38, v36
	s_nop 0
	v_fma_f32 v39, -v36, v38, 1.0
	v_fmac_f32_e32 v38, v39, v38
	v_div_scale_f32 v39, vcc, v37, v7, v37
	v_mul_f32_e32 v40, v39, v38
	v_fma_f32 v41, -v36, v40, v39
	v_fmac_f32_e32 v40, v41, v38
	v_fma_f32 v36, -v36, v40, v39
	v_div_fmas_f32 v36, v36, v38, v40
	v_div_fixup_f32 v7, v36, v7, v37
	v_lshlrev_b32_e32 v36, 16, v20
	v_mul_f32_e32 v38, 0xbfb8aa3b, v36
	v_exp_f32_e32 v38, v38
	v_and_b32_e32 v20, 0xffff0000, v20
	v_lshlrev_b32_e32 v37, 16, v21
	v_and_b32_e32 v21, 0xffff0000, v21
	v_add_f32_e32 v38, 1.0, v38
	v_div_scale_f32 v39, s[0:1], v38, v38, v36
	v_rcp_f32_e32 v40, v39
	v_mul_f32_e32 v6, v7, v6
	v_cvt_pk_bf16_f32 v5, v5, v6
	global_store_dwordx2 v[12:13], v[4:5], off offset:2560
	v_fma_f32 v41, -v39, v40, 1.0
	v_fmac_f32_e32 v40, v41, v40
	v_div_scale_f32 v41, vcc, v36, v38, v36
	v_mul_f32_e32 v42, v41, v40
	v_fma_f32 v43, -v39, v42, v41
	v_fmac_f32_e32 v42, v43, v40
	v_fma_f32 v39, -v39, v42, v41
	v_div_fmas_f32 v39, v39, v40, v42
	v_div_fixup_f32 v36, v39, v38, v36
	v_mul_f32_e32 v38, 0xbfb8aa3b, v20
	v_exp_f32_e32 v38, v38
	ds_read_b128 v[4:7], v83 offset:6144
	v_add_f32_e32 v38, 1.0, v38
	v_div_scale_f32 v39, s[0:1], v38, v38, v20
	v_rcp_f32_e32 v40, v39
	s_nop 0
	v_fma_f32 v41, -v39, v40, 1.0
	v_fmac_f32_e32 v40, v41, v40
	v_div_scale_f32 v41, vcc, v20, v38, v20
	v_mul_f32_e32 v42, v41, v40
	v_fma_f32 v43, -v39, v42, v41
	v_fmac_f32_e32 v42, v43, v40
	v_fma_f32 v39, -v39, v42, v41
	v_div_fmas_f32 v39, v39, v40, v42
	v_div_fixup_f32 v38, v39, v38, v20
	v_mul_f32_e32 v20, 0xbfb8aa3b, v37
	v_exp_f32_e32 v20, v20
	s_nop 0
	v_add_f32_e32 v20, 1.0, v20
	v_div_scale_f32 v39, s[0:1], v20, v20, v37
	v_rcp_f32_e32 v40, v39
	s_nop 0
	v_fma_f32 v41, -v39, v40, 1.0
	v_fmac_f32_e32 v40, v41, v40
	v_div_scale_f32 v41, vcc, v37, v20, v37
	v_mul_f32_e32 v42, v41, v40
	v_fma_f32 v43, -v39, v42, v41
	v_fmac_f32_e32 v42, v43, v40
	v_fma_f32 v39, -v39, v42, v41
	v_div_fmas_f32 v39, v39, v40, v42
	v_div_fixup_f32 v37, v39, v20, v37
	v_mul_f32_e32 v20, 0xbfb8aa3b, v21
	v_exp_f32_e32 v20, v20
	s_nop 0
	v_add_f32_e32 v20, 1.0, v20
	v_div_scale_f32 v39, s[0:1], v20, v20, v21
	v_rcp_f32_e32 v40, v39
	s_nop 0
	v_fma_f32 v41, -v39, v40, 1.0
	v_fmac_f32_e32 v40, v41, v40
	v_div_scale_f32 v41, vcc, v21, v20, v21
	v_mul_f32_e32 v42, v41, v40
	v_fma_f32 v43, -v39, v42, v41
	v_fmac_f32_e32 v42, v43, v40
	v_fma_f32 v39, -v39, v42, v41
	v_div_fmas_f32 v39, v39, v40, v42
	v_div_fixup_f32 v39, v39, v20, v21
	v_mov_b32_e32 v20, v32
	v_mov_b32_e32 v21, v28
	v_mov_b32_e32 v28, v33
	v_pk_add_f32 v[20:21], v[20:21], v[28:29]
	v_mov_b32_e32 v28, v30
	v_mov_b32_e32 v29, v26
	v_pk_add_f32 v[20:21], v[28:29], v[20:21]
	v_mov_b32_e32 v26, v31
	v_pk_add_f32 v[20:21], v[26:27], v[20:21]
	ds_bpermute_b32 v27, v84, v21
	ds_bpermute_b32 v26, v84, v20
	s_waitcnt lgkmcnt(0)
	v_pk_add_f32 v[20:21], v[20:21], v[26:27]
	ds_bpermute_b32 v27, v85, v21
	ds_bpermute_b32 v26, v85, v20
	s_waitcnt lgkmcnt(0)
	v_pk_add_f32 v[20:21], v[20:21], v[26:27]
	ds_bpermute_b32 v27, v86, v21
	ds_bpermute_b32 v26, v86, v20
	s_waitcnt lgkmcnt(0)
	v_pk_add_f32 v[20:21], v[20:21], v[26:27]
	ds_bpermute_b32 v27, v87, v21
	ds_bpermute_b32 v26, v87, v20
	s_waitcnt lgkmcnt(0)
	v_pk_add_f32 v[20:21], v[20:21], v[26:27]
	ds_bpermute_b32 v27, v88, v21
	ds_bpermute_b32 v26, v88, v20
	s_waitcnt lgkmcnt(0)
	v_pk_add_f32 v[20:21], v[20:21], v[26:27]
	ds_bpermute_b32 v27, v89, v21
	ds_bpermute_b32 v26, v89, v20
	s_waitcnt lgkmcnt(0)
	v_pk_add_f32 v[20:21], v[20:21], v[26:27]
	s_nop 0
	v_pk_fma_f32 v[20:21], v[20:21], s[34:35], v[34:35] op_sel_hi:[1,0,0]
	s_nop 0
	v_mul_f32_e32 v26, 0x4b800000, v21
	v_cmp_gt_f32_e64 s[0:1], s72, v21
	v_cmp_gt_f32_e32 vcc, s72, v20
	s_nop 0
	v_cndmask_b32_e64 v21, v21, v26, s[0:1]
	v_rsq_f32_e32 v21, v21
	s_nop 0
	v_mul_f32_e32 v26, 0x45800000, v21
	v_cndmask_b32_e64 v21, v21, v26, s[0:1]
	v_mul_f32_e32 v22, v22, v21
	v_mul_f32_e32 v4, v22, v4
	v_mul_f32_e32 v22, v23, v21
	v_mul_f32_e32 v5, v22, v5
	v_mul_f32_e32 v4, v36, v4
	v_mul_f32_e32 v5, v38, v5
	v_cvt_pk_bf16_f32 v4, v4, v5
	v_mul_f32_e32 v5, v24, v21
	v_mul_f32_e32 v5, v5, v6
	v_mul_f32_e32 v6, v25, v21
	v_mul_f32_e32 v5, v37, v5
	v_mul_f32_e32 v6, v6, v7
	v_mul_f32_e32 v6, v39, v6
	v_cvt_pk_bf16_f32 v5, v5, v6
	global_store_dwordx2 v[12:13], v[4:5], off offset:3072
	v_mul_f32_e32 v4, 0x4b800000, v20
	v_cndmask_b32_e32 v4, v20, v4, vcc
	v_rsq_f32_e32 v4, v4
	v_lshlrev_b32_e32 v21, 16, v18
	v_and_b32_e32 v22, 0xffff0000, v18
	v_lshlrev_b32_e32 v23, 16, v19
	v_mul_f32_e32 v5, 0x45800000, v4
	v_cndmask_b32_e32 v20, v4, v5, vcc
	ds_read_b128 v[4:7], v83 offset:7168
	v_mul_f32_e32 v16, v16, v20
	v_and_b32_e32 v18, 0xffff0000, v19
	s_waitcnt lgkmcnt(0)
	v_mul_f32_e32 v4, v16, v4
	v_mul_f32_e32 v16, 0xbfb8aa3b, v21
	v_exp_f32_e32 v16, v16
	s_nop 0
	v_add_f32_e32 v16, 1.0, v16
	v_div_scale_f32 v19, s[0:1], v16, v16, v21
	v_rcp_f32_e32 v24, v19
	s_nop 0
	v_fma_f32 v25, -v19, v24, 1.0
	v_fmac_f32_e32 v24, v25, v24
	v_div_scale_f32 v25, vcc, v21, v16, v21
	v_mul_f32_e32 v26, v25, v24
	v_fma_f32 v27, -v19, v26, v25
	v_fmac_f32_e32 v26, v27, v24
	v_fma_f32 v19, -v19, v26, v25
	v_div_fmas_f32 v19, v19, v24, v26
	v_div_fixup_f32 v16, v19, v16, v21
	v_mul_f32_e32 v4, v16, v4
	v_mul_f32_e32 v16, v17, v20
	v_mul_f32_e32 v5, v16, v5
	v_mul_f32_e32 v16, 0xbfb8aa3b, v22
	v_exp_f32_e32 v16, v16
	s_nop 0
	v_add_f32_e32 v16, 1.0, v16
	v_div_scale_f32 v17, s[0:1], v16, v16, v22
	v_rcp_f32_e32 v19, v17
	s_nop 0
	v_fma_f32 v21, -v17, v19, 1.0
	v_fmac_f32_e32 v19, v21, v19
	v_div_scale_f32 v21, vcc, v22, v16, v22
	v_mul_f32_e32 v24, v21, v19
	v_fma_f32 v25, -v17, v24, v21
	v_fmac_f32_e32 v24, v25, v19
	v_fma_f32 v17, -v17, v24, v21
	v_div_fmas_f32 v17, v17, v19, v24
	v_div_fixup_f32 v16, v17, v16, v22
	v_mul_f32_e32 v5, v16, v5
	v_cvt_pk_bf16_f32 v4, v4, v5
	v_mul_f32_e32 v5, v14, v20
	v_mul_f32_e32 v5, v5, v6
	v_mul_f32_e32 v6, 0xbfb8aa3b, v23
	v_exp_f32_e32 v6, v6
	s_nop 0
	v_add_f32_e32 v6, 1.0, v6
	v_div_scale_f32 v14, s[0:1], v6, v6, v23
	v_rcp_f32_e32 v16, v14
	s_nop 0
	v_fma_f32 v17, -v14, v16, 1.0
	v_fmac_f32_e32 v16, v17, v16
	v_div_scale_f32 v17, vcc, v23, v6, v23
	v_mul_f32_e32 v19, v17, v16
	v_fma_f32 v21, -v14, v19, v17
	v_fmac_f32_e32 v19, v21, v16
	v_fma_f32 v14, -v14, v19, v17
	v_div_fmas_f32 v14, v14, v16, v19
	v_div_fixup_f32 v6, v14, v6, v23
	v_mul_f32_e32 v5, v6, v5
	v_mul_f32_e32 v6, v15, v20
	v_mul_f32_e32 v6, v6, v7
	v_mul_f32_e32 v7, 0xbfb8aa3b, v18
	v_exp_f32_e32 v7, v7
	s_nop 0
	v_add_f32_e32 v7, 1.0, v7
	v_div_scale_f32 v15, s[0:1], v7, v7, v18
	v_rcp_f32_e32 v14, v15
	s_movk_i32 s0, 0x1fff
	v_fma_f32 v16, -v15, v14, 1.0
	v_fmac_f32_e32 v14, v16, v14
	v_div_scale_f32 v16, vcc, v18, v7, v18
	v_mul_f32_e32 v17, v16, v14
	v_fma_f32 v19, -v15, v17, v16
	v_fmac_f32_e32 v17, v19, v14
	v_fma_f32 v15, -v15, v17, v16
	v_div_fmas_f32 v14, v15, v14, v17
	v_cmp_lt_i32_e32 vcc, s0, v82
	v_div_fixup_f32 v7, v14, v7, v18
	s_or_b64 s[6:7], vcc, s[6:7]
	v_mul_f32_e32 v6, v7, v6
	v_cvt_pk_bf16_f32 v5, v5, v6
	global_store_dwordx2 v[12:13], v[4:5], off offset:3584
	s_andn2_b64 exec, exec, s[6:7]
	s_cbranch_execnz .LBB0_503
